# v34 + fused-epilogue row-sum reductions across lane^16/lane^32 via v_permlane16/32_swap instead of ds_bpermute
# speedup vs baseline: 1.0153x; 1.0016x over previous
.LBB0_1723:
	v_and_b32_e32 v130, 64, v228
	v_xor_b32_e32 v129, 16, v228
	v_add_u32_e32 v130, 64, v130
	v_cmp_lt_i32_e32 vcc, v129, v130
	v_mul_f32_e32 v131, v55, v55
	v_fmac_f32_e32 v131, v54, v54
	v_cndmask_b32_e32 v129, v228, v129, vcc
	v_lshlrev_b32_e32 v195, 2, v129
	v_mul_f32_e32 v129, v53, v53
	v_fmac_f32_e32 v129, v52, v52
	v_add_f32_e32 v129, v129, v131
	v_mul_f32_e32 v131, v49, v49
	v_mul_f32_e32 v132, v51, v51
	v_fmac_f32_e32 v131, v48, v48
	v_fmac_f32_e32 v132, v50, v50
	v_add_f32_e32 v131, v131, v132
	v_add_f32_e32 v129, v131, v129
	v_mul_f32_e32 v131, v61, v61
	v_mul_f32_e32 v132, v63, v63
	v_fmac_f32_e32 v131, v60, v60
	v_fmac_f32_e32 v132, v62, v62
	v_add_f32_e32 v131, v131, v132
	v_add_f32_e32 v129, v131, v129
	v_mul_f32_e32 v131, v57, v57
	v_mul_f32_e32 v132, v59, v59
	v_fmac_f32_e32 v131, v56, v56
	v_fmac_f32_e32 v132, v58, v58
	v_add_f32_e32 v131, v131, v132
	v_add_f32_e32 v129, v131, v129
	v_mov_b32_e32 v131, v129
	s_nop 1
	v_permlane16_swap_b32 v131, v129
	v_xor_b32_e32 v132, 32, v228
	v_cmp_lt_i32_e32 vcc, v132, v130
	v_and_b32_e32 v128, 63, v142
	s_lshl_b32 s3, s36, 2
	v_cndmask_b32_e32 v130, v228, v132, vcc
	v_lshlrev_b32_e32 v196, 2, v130
	s_waitcnt lgkmcnt(0)
	v_add_f32_e32 v129, v129, v131
	v_mov_b32_e32 v130, v129
	s_nop 1
	v_permlane32_swap_b32 v130, v129
	v_cmp_gt_u32_e64 s[6:7], 16, v128
	s_add_i32 s3, s3, 0
	s_barrier
	s_and_saveexec_b64 s[8:9], s[6:7]
	s_cbranch_execz .LBB0_1725
	s_lshl_b32 s4, s2, 10
	s_add_i32 s4, s3, s4
	v_lshl_add_u32 v131, v145, 4, s4
	s_waitcnt lgkmcnt(0)
	v_add_f32_e32 v129, v129, v130
	ds_write_b32 v131, v129
.LBB0_1725:
	s_or_b64 exec, exec, s[8:9]
	v_mul_f32_e32 v129, v73, v73
	s_waitcnt lgkmcnt(0)
	v_mul_f32_e32 v130, v75, v75
	v_fmac_f32_e32 v129, v72, v72
	v_fmac_f32_e32 v130, v74, v74
	v_add_f32_e32 v129, v129, v130
	v_mul_f32_e32 v130, v77, v77
	v_mul_f32_e32 v131, v79, v79
	v_fmac_f32_e32 v130, v76, v76
	v_fmac_f32_e32 v131, v78, v78
	v_add_f32_e32 v130, v130, v131
	v_add_f32_e32 v129, v130, v129
	v_mul_f32_e32 v130, v89, v89
	v_mul_f32_e32 v131, v91, v91
	v_fmac_f32_e32 v130, v88, v88
	v_fmac_f32_e32 v131, v90, v90
	v_add_f32_e32 v130, v130, v131
	v_add_f32_e32 v129, v130, v129
	v_mul_f32_e32 v130, v93, v93
	v_mul_f32_e32 v131, v95, v95
	v_fmac_f32_e32 v130, v92, v92
	v_fmac_f32_e32 v131, v94, v94
	v_add_f32_e32 v130, v130, v131
	v_add_f32_e32 v129, v130, v129
	v_mov_b32_e32 v130, v129
	s_nop 1
	v_permlane16_swap_b32 v130, v129
	s_waitcnt lgkmcnt(0)
	v_add_f32_e32 v129, v129, v130
	v_mov_b32_e32 v130, v129
	s_nop 1
	v_permlane32_swap_b32 v130, v129
	s_and_saveexec_b64 s[8:9], s[6:7]
	s_cbranch_execz .LBB0_1727
	s_lshl_b32 s4, s2, 10
	s_add_i32 s4, s3, s4
	v_lshl_add_u32 v131, v145, 4, s4
	s_waitcnt lgkmcnt(0)
	v_add_f32_e32 v129, v129, v130
	ds_write_b32 v131, v129 offset:256
.LBB0_1727:
	s_or_b64 exec, exec, s[8:9]
	v_mul_f32_e32 v129, v105, v105
	s_waitcnt lgkmcnt(0)
	v_mul_f32_e32 v130, v107, v107
	v_fmac_f32_e32 v129, v104, v104
	v_fmac_f32_e32 v130, v106, v106
	v_add_f32_e32 v129, v129, v130
	v_mul_f32_e32 v130, v101, v101
	v_mul_f32_e32 v131, v103, v103
	v_fmac_f32_e32 v130, v100, v100
	v_fmac_f32_e32 v131, v102, v102
	v_add_f32_e32 v130, v130, v131
	v_add_f32_e32 v129, v130, v129
	v_mul_f32_e32 v130, v117, v117
	v_mul_f32_e32 v131, v119, v119
	v_fmac_f32_e32 v130, v116, v116
	v_fmac_f32_e32 v131, v118, v118
	v_add_f32_e32 v130, v130, v131
	v_add_f32_e32 v129, v130, v129
	v_mul_f32_e32 v130, v113, v113
	v_mul_f32_e32 v131, v115, v115
	v_fmac_f32_e32 v130, v112, v112
	v_fmac_f32_e32 v131, v114, v114
	v_add_f32_e32 v130, v130, v131
	v_add_f32_e32 v129, v130, v129
	v_mov_b32_e32 v130, v129
	s_nop 1
	v_permlane16_swap_b32 v130, v129
	s_waitcnt lgkmcnt(0)
	v_add_f32_e32 v129, v129, v130
	v_mov_b32_e32 v130, v129
	s_nop 1
	v_permlane32_swap_b32 v130, v129
	s_and_saveexec_b64 s[8:9], s[6:7]
	s_cbranch_execz .LBB0_1729
	s_lshl_b32 s4, s2, 10
	s_add_i32 s4, s3, s4
	v_lshl_add_u32 v131, v145, 4, s4
	s_waitcnt lgkmcnt(0)
	v_add_f32_e32 v129, v129, v130
	ds_write_b32 v131, v129 offset:512
.LBB0_1729:
	s_or_b64 exec, exec, s[8:9]
	v_mul_f32_e32 v129, v125, v125
	s_waitcnt lgkmcnt(0)
	v_mul_f32_e32 v130, v127, v127
	v_fmac_f32_e32 v129, v124, v124
	v_fmac_f32_e32 v130, v126, v126
	v_add_f32_e32 v129, v129, v130
	v_mul_f32_e32 v130, v121, v121
	v_mul_f32_e32 v131, v123, v123
	v_fmac_f32_e32 v130, v120, v120
	v_fmac_f32_e32 v131, v122, v122
	v_add_f32_e32 v130, v130, v131
	v_add_f32_e32 v129, v130, v129
	v_mul_f32_e32 v130, v109, v109
	v_mul_f32_e32 v131, v111, v111
	v_fmac_f32_e32 v130, v108, v108
	v_fmac_f32_e32 v131, v110, v110
	v_add_f32_e32 v130, v130, v131
	v_add_f32_e32 v129, v130, v129
	v_mul_f32_e32 v130, v97, v97
	v_mul_f32_e32 v131, v99, v99
	v_fmac_f32_e32 v130, v96, v96
	v_fmac_f32_e32 v131, v98, v98
	v_add_f32_e32 v130, v130, v131
	v_add_f32_e32 v129, v130, v129
	v_mov_b32_e32 v130, v129
	s_nop 1
	v_permlane16_swap_b32 v130, v129
	s_waitcnt lgkmcnt(0)
	v_add_f32_e32 v129, v129, v130
	v_mov_b32_e32 v130, v129
	s_nop 1
	v_permlane32_swap_b32 v130, v129
	s_and_saveexec_b64 s[8:9], s[6:7]
	s_cbranch_execz .LBB0_1731
	s_lshl_b32 s4, s2, 10
	s_add_i32 s4, s3, s4
	v_lshl_add_u32 v131, v145, 4, s4
	s_waitcnt lgkmcnt(0)
	v_add_f32_e32 v129, v129, v130
	ds_write_b32 v131, v129 offset:768
.LBB0_1731:
	s_or_b64 exec, exec, s[8:9]
	v_mul_f32_e32 v129, v85, v85
	s_waitcnt lgkmcnt(0)
	v_mul_f32_e32 v130, v87, v87
	v_fmac_f32_e32 v129, v84, v84
	v_fmac_f32_e32 v130, v86, v86
	v_add_f32_e32 v129, v129, v130
	v_mul_f32_e32 v130, v81, v81
	v_mul_f32_e32 v131, v83, v83
	v_fmac_f32_e32 v130, v80, v80
	v_fmac_f32_e32 v131, v82, v82
	v_add_f32_e32 v130, v130, v131
	v_add_f32_e32 v129, v130, v129
	v_mul_f32_e32 v130, v69, v69
	v_mul_f32_e32 v131, v71, v71
	v_fmac_f32_e32 v130, v68, v68
	v_fmac_f32_e32 v131, v70, v70
	v_add_f32_e32 v130, v130, v131
	v_add_f32_e32 v129, v130, v129
	v_mul_f32_e32 v130, v65, v65
	v_mul_f32_e32 v131, v67, v67
	v_fmac_f32_e32 v130, v64, v64
	v_fmac_f32_e32 v131, v66, v66
	v_add_f32_e32 v130, v130, v131
	v_add_f32_e32 v129, v130, v129
	v_mov_b32_e32 v130, v129
	s_nop 1
	v_permlane16_swap_b32 v130, v129
	s_waitcnt lgkmcnt(0)
	v_add_f32_e32 v129, v129, v130
	v_mov_b32_e32 v130, v129
	s_nop 1
	v_permlane32_swap_b32 v130, v129
	s_and_saveexec_b64 s[8:9], s[6:7]
	s_cbranch_execz .LBB0_1733
	s_lshl_b32 s4, s2, 10
	s_add_i32 s4, s3, s4
	v_lshl_add_u32 v131, v145, 4, s4
	s_waitcnt lgkmcnt(0)
	v_add_f32_e32 v129, v129, v130
	ds_write_b32 v131, v129 offset:2048
.LBB0_1733:
	s_or_b64 exec, exec, s[8:9]
	v_mul_f32_e32 v129, v45, v45
	s_waitcnt lgkmcnt(0)
	v_mul_f32_e32 v130, v47, v47
	v_fmac_f32_e32 v129, v44, v44
	v_fmac_f32_e32 v130, v46, v46
	v_add_f32_e32 v129, v129, v130
	v_mul_f32_e32 v130, v41, v41
	v_mul_f32_e32 v131, v43, v43
	v_fmac_f32_e32 v130, v40, v40
	v_fmac_f32_e32 v131, v42, v42
	v_add_f32_e32 v130, v130, v131
	v_add_f32_e32 v129, v130, v129
	v_mul_f32_e32 v130, v37, v37
	v_mul_f32_e32 v131, v39, v39
	v_fmac_f32_e32 v130, v36, v36
	v_fmac_f32_e32 v131, v38, v38
	v_add_f32_e32 v130, v130, v131
	v_add_f32_e32 v129, v130, v129
	v_mul_f32_e32 v130, v33, v33
	v_mul_f32_e32 v131, v35, v35
	v_fmac_f32_e32 v130, v32, v32
	v_fmac_f32_e32 v131, v34, v34
	v_add_f32_e32 v130, v130, v131
	v_add_f32_e32 v129, v130, v129
	v_mov_b32_e32 v130, v129
	s_nop 1
	v_permlane16_swap_b32 v130, v129
	s_waitcnt lgkmcnt(0)
	v_add_f32_e32 v129, v129, v130
	v_mov_b32_e32 v130, v129
	s_nop 1
	v_permlane32_swap_b32 v130, v129
	s_and_saveexec_b64 s[8:9], s[6:7]
	s_cbranch_execz .LBB0_1735
	s_lshl_b32 s4, s2, 10
	s_add_i32 s4, s3, s4
	v_lshl_add_u32 v131, v145, 4, s4
	s_waitcnt lgkmcnt(0)
	v_add_f32_e32 v129, v129, v130
	ds_write_b32 v131, v129 offset:2304
.LBB0_1735:
	s_or_b64 exec, exec, s[8:9]
	v_mul_f32_e32 v129, v29, v29
	s_waitcnt lgkmcnt(0)
	v_mul_f32_e32 v130, v31, v31
	v_fmac_f32_e32 v129, v28, v28
	v_fmac_f32_e32 v130, v30, v30
	v_add_f32_e32 v129, v129, v130
	v_mul_f32_e32 v130, v25, v25
	v_mul_f32_e32 v131, v27, v27
	v_fmac_f32_e32 v130, v24, v24
	v_fmac_f32_e32 v131, v26, v26
	v_add_f32_e32 v130, v130, v131
	v_add_f32_e32 v129, v130, v129
	v_mul_f32_e32 v130, v21, v21
	v_mul_f32_e32 v131, v23, v23
	v_fmac_f32_e32 v130, v20, v20
	v_fmac_f32_e32 v131, v22, v22
	v_add_f32_e32 v130, v130, v131
	v_add_f32_e32 v129, v130, v129
	v_mul_f32_e32 v130, v17, v17
	v_mul_f32_e32 v131, v19, v19
	v_fmac_f32_e32 v130, v16, v16
	v_fmac_f32_e32 v131, v18, v18
	v_add_f32_e32 v130, v130, v131
	v_add_f32_e32 v129, v130, v129
	v_mov_b32_e32 v130, v129
	s_nop 1
	v_permlane16_swap_b32 v130, v129
	s_waitcnt lgkmcnt(0)
	v_add_f32_e32 v129, v129, v130
	v_mov_b32_e32 v130, v129
	s_nop 1
	v_permlane32_swap_b32 v130, v129
	s_and_saveexec_b64 s[8:9], s[6:7]
	s_cbranch_execz .LBB0_1737
	s_lshl_b32 s4, s2, 10
	s_add_i32 s4, s3, s4
	v_lshl_add_u32 v131, v145, 4, s4
	s_waitcnt lgkmcnt(0)
	v_add_f32_e32 v129, v129, v130
	ds_write_b32 v131, v129 offset:2560
.LBB0_1737:
	s_or_b64 exec, exec, s[8:9]
	v_mul_f32_e32 v129, v13, v13
	s_waitcnt lgkmcnt(0)
	v_mul_f32_e32 v130, v15, v15
	v_fmac_f32_e32 v129, v12, v12
	v_fmac_f32_e32 v130, v14, v14
	v_add_f32_e32 v129, v129, v130
	v_mul_f32_e32 v130, v9, v9
	v_mul_f32_e32 v131, v11, v11
	v_fmac_f32_e32 v130, v8, v8
	v_fmac_f32_e32 v131, v10, v10
	v_add_f32_e32 v130, v130, v131
	v_add_f32_e32 v129, v130, v129
	v_mul_f32_e32 v130, v5, v5
	v_mul_f32_e32 v131, v7, v7
	v_fmac_f32_e32 v130, v4, v4
	v_fmac_f32_e32 v131, v6, v6
	v_add_f32_e32 v130, v130, v131
	v_add_f32_e32 v129, v130, v129
	v_mul_f32_e32 v130, v1, v1
	v_mul_f32_e32 v131, v3, v3
	v_fmac_f32_e32 v130, v0, v0
	v_fmac_f32_e32 v131, v2, v2
	v_add_f32_e32 v130, v130, v131
	v_add_f32_e32 v129, v130, v129
	v_mov_b32_e32 v130, v129
	s_nop 1
	v_permlane16_swap_b32 v130, v129
	s_waitcnt lgkmcnt(0)
	v_add_f32_e32 v129, v129, v130
	v_mov_b32_e32 v130, v129
	s_nop 1
	v_permlane32_swap_b32 v130, v129
	s_and_saveexec_b64 s[8:9], s[6:7]
	s_cbranch_execz .LBB0_1739
	s_lshl_b32 s4, s2, 10
	s_add_i32 s4, s3, s4
	v_lshl_add_u32 v131, v145, 4, s4
	s_waitcnt lgkmcnt(0)
	v_add_f32_e32 v129, v129, v130
	ds_write_b32 v131, v129 offset:2816

.LBB0_1768:
	s_or_b64 exec, exec, s[26:27]
	s_lshl_b32 s14, s36, 5
	s_lshl_b32 s15, s22, 8
	v_lshrrev_b32_e32 v128, 1, v142
	s_or_b32 s14, s15, s14
	v_and_or_b32 v146, v128, 24, s14
	v_ashrrev_i32_e32 v147, 31, v146
	v_lshlrev_b64 v[152:153], 2, v[146:147]
	v_lshl_add_u64 v[132:133], s[60:61], 0, v[152:153]
	v_lshl_add_u64 v[182:183], s[80:81], 0, v[152:153]
	v_lshl_add_u32 v152, s20, 8, v150
	v_ashrrev_i32_e32 v153, 31, v152
	v_lshl_add_u32 v194, v150, 2, 0
	v_lshlrev_b64 v[150:151], 12, v[152:153]
	s_waitcnt lgkmcnt(0)
	s_barrier
	v_lshl_add_u64 v[150:151], v[182:183], 0, v[150:151]
	global_load_dwordx4 v[136:139], v[132:133], off offset:16
	global_load_dwordx4 v[140:143], v[132:133], off
	s_waitcnt lgkmcnt(0)
	global_load_dwordx4 v[128:131], v[132:133], off offset:528
	s_nop 0
	global_load_dwordx4 v[132:135], v[132:133], off offset:512
	ds_read_b32 v158, v194 offset:4096
	global_load_dwordx4 v[154:157], v[150:151], off offset:16
	global_load_dwordx4 v[172:175], v[150:151], off
	v_cmp_eq_u32_e32 vcc, 0, v197
	v_add_u32_e32 v192, 0xb0, v152
	v_ashrrev_i32_e32 v193, 31, v192
	s_waitcnt lgkmcnt(0)
	v_pk_mul_f32 v[52:53], v[52:53], v[158:159] op_sel_hi:[1,0]
	v_pk_mul_f32 v[54:55], v[54:55], v[158:159] op_sel_hi:[1,0]
	v_pk_mul_f32 v[48:49], v[48:49], v[158:159] op_sel_hi:[1,0]
	v_pk_mul_f32 v[50:51], v[50:51], v[158:159] op_sel_hi:[1,0]
	v_pk_mul_f32 v[56:57], v[56:57], v[158:159] op_sel_hi:[1,0]
	v_pk_mul_f32 v[60:61], v[60:61], v[158:159] op_sel_hi:[1,0]
	v_pk_mul_f32 v[62:63], v[62:63], v[158:159] op_sel_hi:[1,0]
	v_pk_mul_f32 v[58:59], v[58:59], v[158:159] op_sel_hi:[1,0]
	s_waitcnt vmcnt(0)
	v_pk_fma_f32 v[50:51], v[138:139], v[50:51], v[156:157]
	v_pk_fma_f32 v[54:55], v[142:143], v[54:55], v[174:175]
	v_pk_fma_f32 v[52:53], v[140:141], v[52:53], v[172:173]
	v_pk_fma_f32 v[48:49], v[136:137], v[48:49], v[154:155]
	global_load_dwordx4 v[154:157], v[150:151], off offset:528
	global_load_dwordx4 v[172:175], v[150:151], off offset:512
	v_cndmask_b32_e32 v55, v235, v55, vcc
	v_cndmask_b32_e32 v54, v235, v54, vcc
	v_cndmask_b32_e32 v53, v235, v53, vcc
	v_cndmask_b32_e32 v52, v235, v52, vcc
	v_cndmask_b32_e32 v51, v235, v51, vcc
	v_cndmask_b32_e32 v50, v235, v50, vcc
	v_cndmask_b32_e32 v49, v235, v49, vcc
	v_cndmask_b32_e32 v48, v235, v48, vcc
	s_waitcnt vmcnt(1)
	v_pk_fma_f32 v[56:57], v[128:129], v[56:57], v[154:155]
	v_add_u32_e32 v154, 16, v152
	v_ashrrev_i32_e32 v155, 31, v154
	s_waitcnt vmcnt(0)
	v_pk_fma_f32 v[62:63], v[134:135], v[62:63], v[174:175]
	v_pk_fma_f32 v[60:61], v[132:133], v[60:61], v[172:173]
	v_pk_fma_f32 v[58:59], v[130:131], v[58:59], v[156:157]
	v_lshlrev_b64 v[156:157], 12, v[154:155]
	v_cndmask_b32_e32 v63, v235, v63, vcc
	v_cndmask_b32_e32 v62, v235, v62, vcc
	v_cndmask_b32_e32 v61, v235, v61, vcc
	v_cndmask_b32_e32 v60, v235, v60, vcc
	v_cndmask_b32_e32 v59, v235, v59, vcc
	v_cndmask_b32_e32 v58, v235, v58, vcc
	v_cndmask_b32_e32 v57, v235, v57, vcc
	v_cndmask_b32_e32 v56, v235, v56, vcc
	v_lshl_add_u64 v[156:157], v[182:183], 0, v[156:157]
	ds_read_b32 v158, v194 offset:4160
	global_load_dwordx4 v[172:175], v[156:157], off offset:16
	global_load_dwordx4 v[176:179], v[156:157], off
	s_waitcnt lgkmcnt(0)
	v_pk_mul_f32 v[72:73], v[72:73], v[158:159] op_sel_hi:[1,0]
	v_pk_mul_f32 v[74:75], v[74:75], v[158:159] op_sel_hi:[1,0]
	v_pk_mul_f32 v[76:77], v[76:77], v[158:159] op_sel_hi:[1,0]
	v_pk_mul_f32 v[78:79], v[78:79], v[158:159] op_sel_hi:[1,0]
	v_pk_mul_f32 v[92:93], v[92:93], v[158:159] op_sel_hi:[1,0]
	v_pk_mul_f32 v[88:89], v[88:89], v[158:159] op_sel_hi:[1,0]
	v_pk_mul_f32 v[90:91], v[90:91], v[158:159] op_sel_hi:[1,0]
	v_pk_mul_f32 v[94:95], v[94:95], v[158:159] op_sel_hi:[1,0]
	s_waitcnt vmcnt(1)
	v_pk_fma_f32 v[78:79], v[138:139], v[78:79], v[174:175]
	s_waitcnt vmcnt(0)
	v_pk_fma_f32 v[74:75], v[142:143], v[74:75], v[178:179]
	v_pk_fma_f32 v[72:73], v[140:141], v[72:73], v[176:177]
	v_pk_fma_f32 v[76:77], v[136:137], v[76:77], v[172:173]
	global_load_dwordx4 v[172:175], v[156:157], off offset:528
	global_load_dwordx4 v[176:179], v[156:157], off offset:512
	v_cndmask_b32_e32 v75, v235, v75, vcc
	v_cndmask_b32_e32 v74, v235, v74, vcc
	v_cndmask_b32_e32 v73, v235, v73, vcc
	v_cndmask_b32_e32 v72, v235, v72, vcc
	v_cndmask_b32_e32 v79, v235, v79, vcc
	v_cndmask_b32_e32 v78, v235, v78, vcc
	v_cndmask_b32_e32 v77, v235, v77, vcc
	v_cndmask_b32_e32 v76, v235, v76, vcc
	s_waitcnt vmcnt(1)
	v_pk_fma_f32 v[92:93], v[128:129], v[92:93], v[172:173]
	v_add_u32_e32 v172, 32, v152
	s_waitcnt vmcnt(0)
	v_pk_fma_f32 v[90:91], v[134:135], v[90:91], v[178:179]
	v_pk_fma_f32 v[88:89], v[132:133], v[88:89], v[176:177]
	v_pk_fma_f32 v[94:95], v[130:131], v[94:95], v[174:175]
	v_ashrrev_i32_e32 v173, 31, v172
	v_cndmask_b32_e32 v91, v235, v91, vcc
	v_cndmask_b32_e32 v90, v235, v90, vcc
	v_cndmask_b32_e32 v89, v235, v89, vcc
	v_cndmask_b32_e32 v88, v235, v88, vcc
	v_cndmask_b32_e32 v95, v235, v95, vcc
	v_cndmask_b32_e32 v94, v235, v94, vcc
	v_cndmask_b32_e32 v93, v235, v93, vcc
	v_cndmask_b32_e32 v92, v235, v92, vcc
	v_lshlrev_b64 v[158:159], 12, v[172:173]
	v_lshl_add_u64 v[158:159], v[182:183], 0, v[158:159]
	ds_read_b32 v160, v194 offset:4224
	global_load_dwordx4 v[174:177], v[158:159], off offset:16
	global_load_dwordx4 v[178:181], v[158:159], off
	s_waitcnt lgkmcnt(0)
	v_pk_mul_f32 v[104:105], v[104:105], v[160:161] op_sel_hi:[1,0]
	v_pk_mul_f32 v[106:107], v[106:107], v[160:161] op_sel_hi:[1,0]
	v_pk_mul_f32 v[100:101], v[100:101], v[160:161] op_sel_hi:[1,0]
	v_pk_mul_f32 v[102:103], v[102:103], v[160:161] op_sel_hi:[1,0]
	v_pk_mul_f32 v[114:115], v[114:115], v[160:161] op_sel_hi:[1,0]
	v_pk_mul_f32 v[116:117], v[116:117], v[160:161] op_sel_hi:[1,0]
	v_pk_mul_f32 v[118:119], v[118:119], v[160:161] op_sel_hi:[1,0]
	v_pk_mul_f32 v[112:113], v[112:113], v[160:161] op_sel_hi:[1,0]
	s_waitcnt vmcnt(1)
	v_pk_fma_f32 v[102:103], v[138:139], v[102:103], v[176:177]
	s_waitcnt vmcnt(0)
	v_pk_fma_f32 v[106:107], v[142:143], v[106:107], v[180:181]
	v_pk_fma_f32 v[104:105], v[140:141], v[104:105], v[178:179]
	v_pk_fma_f32 v[100:101], v[136:137], v[100:101], v[174:175]
	global_load_dwordx4 v[174:177], v[158:159], off offset:528
	global_load_dwordx4 v[178:181], v[158:159], off offset:512
	v_cndmask_b32_e32 v107, v235, v107, vcc
	v_cndmask_b32_e32 v106, v235, v106, vcc
	v_cndmask_b32_e32 v105, v235, v105, vcc
	v_cndmask_b32_e32 v104, v235, v104, vcc
	v_cndmask_b32_e32 v103, v235, v103, vcc
	v_cndmask_b32_e32 v102, v235, v102, vcc
	v_cndmask_b32_e32 v101, v235, v101, vcc
	v_cndmask_b32_e32 v100, v235, v100, vcc
	s_waitcnt vmcnt(1)
	v_pk_fma_f32 v[114:115], v[130:131], v[114:115], v[176:177]
	v_add_u32_e32 v176, 48, v152
	v_ashrrev_i32_e32 v177, 31, v176
	s_waitcnt vmcnt(0)
	v_pk_fma_f32 v[118:119], v[134:135], v[118:119], v[180:181]
	v_pk_fma_f32 v[116:117], v[132:133], v[116:117], v[178:179]
	v_pk_fma_f32 v[112:113], v[128:129], v[112:113], v[174:175]
	v_lshlrev_b64 v[162:163], 12, v[176:177]
	v_cndmask_b32_e32 v119, v235, v119, vcc
	v_cndmask_b32_e32 v118, v235, v118, vcc
	v_cndmask_b32_e32 v117, v235, v117, vcc
	v_cndmask_b32_e32 v116, v235, v116, vcc
	v_cndmask_b32_e32 v115, v235, v115, vcc
	v_cndmask_b32_e32 v114, v235, v114, vcc
	v_cndmask_b32_e32 v113, v235, v113, vcc
	v_cndmask_b32_e32 v112, v235, v112, vcc
	v_lshl_add_u64 v[174:175], v[182:183], 0, v[162:163]
	ds_read_b32 v160, v194 offset:4288
	global_load_dwordx4 v[178:181], v[174:175], off offset:16
	global_load_dwordx4 v[184:187], v[174:175], off
	s_waitcnt lgkmcnt(0)
	v_pk_mul_f32 v[124:125], v[124:125], v[160:161] op_sel_hi:[1,0]
	v_pk_mul_f32 v[126:127], v[126:127], v[160:161] op_sel_hi:[1,0]
	v_pk_mul_f32 v[120:121], v[120:121], v[160:161] op_sel_hi:[1,0]
	v_pk_mul_f32 v[122:123], v[122:123], v[160:161] op_sel_hi:[1,0]
	v_pk_mul_f32 v[98:99], v[98:99], v[160:161] op_sel_hi:[1,0]
	v_pk_mul_f32 v[108:109], v[108:109], v[160:161] op_sel_hi:[1,0]
	v_pk_mul_f32 v[110:111], v[110:111], v[160:161] op_sel_hi:[1,0]
	v_pk_mul_f32 v[96:97], v[96:97], v[160:161] op_sel_hi:[1,0]
	s_waitcnt vmcnt(1)
	v_pk_fma_f32 v[122:123], v[138:139], v[122:123], v[180:181]
	s_waitcnt vmcnt(0)
	v_pk_fma_f32 v[126:127], v[142:143], v[126:127], v[186:187]
	v_pk_fma_f32 v[124:125], v[140:141], v[124:125], v[184:185]
	v_pk_fma_f32 v[120:121], v[136:137], v[120:121], v[178:179]
	global_load_dwordx4 v[178:181], v[174:175], off offset:528
	global_load_dwordx4 v[184:187], v[174:175], off offset:512
	v_cndmask_b32_e32 v127, v235, v127, vcc
	v_cndmask_b32_e32 v126, v235, v126, vcc
	v_cndmask_b32_e32 v125, v235, v125, vcc
	v_cndmask_b32_e32 v124, v235, v124, vcc
	v_cndmask_b32_e32 v123, v235, v123, vcc
	v_cndmask_b32_e32 v122, v235, v122, vcc
	v_cndmask_b32_e32 v121, v235, v121, vcc
	v_cndmask_b32_e32 v120, v235, v120, vcc
	s_waitcnt vmcnt(1)
	v_pk_fma_f32 v[98:99], v[130:131], v[98:99], v[180:181]
	v_add_u32_e32 v180, 0x80, v152
	s_waitcnt vmcnt(0)
	v_pk_fma_f32 v[110:111], v[134:135], v[110:111], v[186:187]
	v_pk_fma_f32 v[108:109], v[132:133], v[108:109], v[184:185]
	v_pk_fma_f32 v[96:97], v[128:129], v[96:97], v[178:179]
	v_ashrrev_i32_e32 v181, 31, v180
	v_cndmask_b32_e32 v111, v235, v111, vcc
	v_cndmask_b32_e32 v110, v235, v110, vcc
	v_cndmask_b32_e32 v109, v235, v109, vcc
	v_cndmask_b32_e32 v108, v235, v108, vcc
	v_cndmask_b32_e32 v99, v235, v99, vcc
	v_cndmask_b32_e32 v98, v235, v98, vcc
	v_cndmask_b32_e32 v97, v235, v97, vcc
	v_cndmask_b32_e32 v96, v235, v96, vcc
	v_lshlrev_b64 v[162:163], 12, v[180:181]
	v_lshl_add_u64 v[178:179], v[182:183], 0, v[162:163]
	ds_read_b32 v160, v194 offset:4608
	global_load_dwordx4 v[184:187], v[178:179], off offset:16
	global_load_dwordx4 v[188:191], v[178:179], off
	s_waitcnt lgkmcnt(0)
	v_pk_mul_f32 v[84:85], v[84:85], v[160:161] op_sel_hi:[1,0]
	v_pk_mul_f32 v[86:87], v[86:87], v[160:161] op_sel_hi:[1,0]
	v_pk_mul_f32 v[80:81], v[80:81], v[160:161] op_sel_hi:[1,0]
	v_pk_mul_f32 v[82:83], v[82:83], v[160:161] op_sel_hi:[1,0]
	v_pk_mul_f32 v[66:67], v[66:67], v[160:161] op_sel_hi:[1,0]
	v_pk_mul_f32 v[68:69], v[68:69], v[160:161] op_sel_hi:[1,0]
	v_pk_mul_f32 v[70:71], v[70:71], v[160:161] op_sel_hi:[1,0]
	v_pk_mul_f32 v[64:65], v[64:65], v[160:161] op_sel_hi:[1,0]
	s_waitcnt vmcnt(1)
	v_pk_fma_f32 v[82:83], v[138:139], v[82:83], v[186:187]
	s_waitcnt vmcnt(0)
	v_pk_fma_f32 v[86:87], v[142:143], v[86:87], v[190:191]
	v_pk_fma_f32 v[84:85], v[140:141], v[84:85], v[188:189]
	v_pk_fma_f32 v[80:81], v[136:137], v[80:81], v[184:185]
	global_load_dwordx4 v[184:187], v[178:179], off offset:528
	global_load_dwordx4 v[188:191], v[178:179], off offset:512
	v_cndmask_b32_e32 v87, v235, v87, vcc
	v_cndmask_b32_e32 v86, v235, v86, vcc
	v_cndmask_b32_e32 v85, v235, v85, vcc
	v_cndmask_b32_e32 v84, v235, v84, vcc
	v_cndmask_b32_e32 v83, v235, v83, vcc
	v_cndmask_b32_e32 v82, v235, v82, vcc
	v_cndmask_b32_e32 v81, v235, v81, vcc
	v_cndmask_b32_e32 v80, v235, v80, vcc
	s_waitcnt vmcnt(1)
	v_pk_fma_f32 v[66:67], v[130:131], v[66:67], v[186:187]
	v_add_u32_e32 v186, 0x90, v152
	v_ashrrev_i32_e32 v187, 31, v186
	s_waitcnt vmcnt(0)
	v_pk_fma_f32 v[70:71], v[134:135], v[70:71], v[190:191]
	v_pk_fma_f32 v[68:69], v[132:133], v[68:69], v[188:189]
	v_pk_fma_f32 v[64:65], v[128:129], v[64:65], v[184:185]
	v_lshlrev_b64 v[162:163], 12, v[186:187]
	v_cndmask_b32_e32 v71, v235, v71, vcc
	v_cndmask_b32_e32 v70, v235, v70, vcc
	v_cndmask_b32_e32 v69, v235, v69, vcc
	v_cndmask_b32_e32 v68, v235, v68, vcc
	v_cndmask_b32_e32 v67, v235, v67, vcc
	v_cndmask_b32_e32 v66, v235, v66, vcc
	v_cndmask_b32_e32 v65, v235, v65, vcc
	v_cndmask_b32_e32 v64, v235, v64, vcc
	v_lshl_add_u64 v[184:185], v[182:183], 0, v[162:163]
	ds_read_b32 v160, v194 offset:4672
	global_load_dwordx4 v[188:191], v[184:185], off offset:16
	global_load_dwordx4 v[200:203], v[184:185], off
	s_waitcnt lgkmcnt(0)
	v_pk_mul_f32 v[44:45], v[44:45], v[160:161] op_sel_hi:[1,0]
	v_pk_mul_f32 v[46:47], v[46:47], v[160:161] op_sel_hi:[1,0]
	v_pk_mul_f32 v[40:41], v[40:41], v[160:161] op_sel_hi:[1,0]
	v_pk_mul_f32 v[42:43], v[42:43], v[160:161] op_sel_hi:[1,0]
	v_pk_mul_f32 v[34:35], v[34:35], v[160:161] op_sel_hi:[1,0]
	v_pk_mul_f32 v[36:37], v[36:37], v[160:161] op_sel_hi:[1,0]
	v_pk_mul_f32 v[38:39], v[38:39], v[160:161] op_sel_hi:[1,0]
	v_pk_mul_f32 v[32:33], v[32:33], v[160:161] op_sel_hi:[1,0]
	s_waitcnt vmcnt(1)
	v_pk_fma_f32 v[42:43], v[138:139], v[42:43], v[190:191]
	s_waitcnt vmcnt(0)
	v_pk_fma_f32 v[46:47], v[142:143], v[46:47], v[202:203]
	v_pk_fma_f32 v[44:45], v[140:141], v[44:45], v[200:201]
	v_pk_fma_f32 v[40:41], v[136:137], v[40:41], v[188:189]
	global_load_dwordx4 v[188:191], v[184:185], off offset:528
	global_load_dwordx4 v[200:203], v[184:185], off offset:512
	v_cndmask_b32_e32 v47, v235, v47, vcc
	v_cndmask_b32_e32 v46, v235, v46, vcc
	v_cndmask_b32_e32 v45, v235, v45, vcc
	v_cndmask_b32_e32 v44, v235, v44, vcc
	v_cndmask_b32_e32 v43, v235, v43, vcc
	v_cndmask_b32_e32 v42, v235, v42, vcc
	v_cndmask_b32_e32 v41, v235, v41, vcc
	v_cndmask_b32_e32 v40, v235, v40, vcc
	s_waitcnt vmcnt(1)
	v_pk_fma_f32 v[34:35], v[130:131], v[34:35], v[190:191]
	v_add_u32_e32 v190, 0xa0, v152
	s_waitcnt vmcnt(0)
	v_pk_fma_f32 v[38:39], v[134:135], v[38:39], v[202:203]
	v_pk_fma_f32 v[36:37], v[132:133], v[36:37], v[200:201]
	v_pk_fma_f32 v[32:33], v[128:129], v[32:33], v[188:189]
	v_ashrrev_i32_e32 v191, 31, v190
	v_cndmask_b32_e32 v39, v235, v39, vcc
	v_cndmask_b32_e32 v38, v235, v38, vcc
	v_cndmask_b32_e32 v37, v235, v37, vcc
	v_cndmask_b32_e32 v36, v235, v36, vcc
	v_cndmask_b32_e32 v35, v235, v35, vcc
	v_cndmask_b32_e32 v34, v235, v34, vcc
	v_cndmask_b32_e32 v33, v235, v33, vcc
	v_cndmask_b32_e32 v32, v235, v32, vcc
	v_lshlrev_b64 v[162:163], 12, v[190:191]
	v_lshl_add_u64 v[188:189], v[182:183], 0, v[162:163]
	ds_read_b32 v160, v194 offset:4736
	global_load_dwordx4 v[200:203], v[188:189], off offset:16
	global_load_dwordx4 v[204:207], v[188:189], off
	v_lshlrev_b64 v[162:163], 12, v[192:193]
	v_lshl_add_u64 v[182:183], v[182:183], 0, v[162:163]
	s_waitcnt lgkmcnt(0)
	v_pk_mul_f32 v[28:29], v[28:29], v[160:161] op_sel_hi:[1,0]
	v_pk_mul_f32 v[30:31], v[30:31], v[160:161] op_sel_hi:[1,0]
	v_pk_mul_f32 v[24:25], v[24:25], v[160:161] op_sel_hi:[1,0]
	v_pk_mul_f32 v[26:27], v[26:27], v[160:161] op_sel_hi:[1,0]
	v_pk_mul_f32 v[20:21], v[20:21], v[160:161] op_sel_hi:[1,0]
	v_pk_mul_f32 v[22:23], v[22:23], v[160:161] op_sel_hi:[1,0]
	v_pk_mul_f32 v[16:17], v[16:17], v[160:161] op_sel_hi:[1,0]
	v_pk_mul_f32 v[18:19], v[18:19], v[160:161] op_sel_hi:[1,0]
	s_waitcnt vmcnt(1)
	v_pk_fma_f32 v[26:27], v[138:139], v[26:27], v[202:203]
	s_waitcnt vmcnt(0)
	v_pk_fma_f32 v[30:31], v[142:143], v[30:31], v[206:207]
	v_pk_fma_f32 v[28:29], v[140:141], v[28:29], v[204:205]
	v_pk_fma_f32 v[24:25], v[136:137], v[24:25], v[200:201]
	global_load_dwordx4 v[200:203], v[188:189], off offset:528
	global_load_dwordx4 v[204:207], v[188:189], off offset:512
	v_cndmask_b32_e32 v31, v235, v31, vcc
	v_cndmask_b32_e32 v30, v235, v30, vcc
	v_cndmask_b32_e32 v29, v235, v29, vcc
	v_cndmask_b32_e32 v28, v235, v28, vcc
	v_cndmask_b32_e32 v27, v235, v27, vcc
	v_cndmask_b32_e32 v26, v235, v26, vcc
	v_cndmask_b32_e32 v25, v235, v25, vcc
	v_cndmask_b32_e32 v24, v235, v24, vcc
	s_waitcnt vmcnt(1)
	v_pk_fma_f32 v[18:19], v[130:131], v[18:19], v[202:203]
	s_waitcnt vmcnt(0)
	v_pk_fma_f32 v[22:23], v[134:135], v[22:23], v[206:207]
	v_pk_fma_f32 v[20:21], v[132:133], v[20:21], v[204:205]
	v_pk_fma_f32 v[16:17], v[128:129], v[16:17], v[200:201]
	v_cndmask_b32_e32 v23, v235, v23, vcc
	v_cndmask_b32_e32 v22, v235, v22, vcc
	v_cndmask_b32_e32 v21, v235, v21, vcc
	v_cndmask_b32_e32 v20, v235, v20, vcc
	v_cndmask_b32_e32 v19, v235, v19, vcc
	v_cndmask_b32_e32 v18, v235, v18, vcc
	v_cndmask_b32_e32 v17, v235, v17, vcc
	v_cndmask_b32_e32 v16, v235, v16, vcc
	ds_read_b32 v160, v194 offset:4800
	global_load_dwordx4 v[200:203], v[182:183], off offset:16
	global_load_dwordx4 v[204:207], v[182:183], off
	s_waitcnt lgkmcnt(0)
	v_pk_mul_f32 v[12:13], v[12:13], v[160:161] op_sel_hi:[1,0]
	v_pk_mul_f32 v[14:15], v[14:15], v[160:161] op_sel_hi:[1,0]
	v_pk_mul_f32 v[8:9], v[8:9], v[160:161] op_sel_hi:[1,0]
	v_pk_mul_f32 v[10:11], v[10:11], v[160:161] op_sel_hi:[1,0]
	v_pk_mul_f32 v[0:1], v[0:1], v[160:161] op_sel_hi:[1,0]
	v_pk_mul_f32 v[2:3], v[2:3], v[160:161] op_sel_hi:[1,0]
	v_pk_mul_f32 v[4:5], v[4:5], v[160:161] op_sel_hi:[1,0]
	v_pk_mul_f32 v[6:7], v[6:7], v[160:161] op_sel_hi:[1,0]
	s_waitcnt vmcnt(1)
	v_pk_fma_f32 v[10:11], v[138:139], v[10:11], v[202:203]
	s_waitcnt vmcnt(0)
	v_pk_fma_f32 v[14:15], v[142:143], v[14:15], v[206:207]
	v_pk_fma_f32 v[12:13], v[140:141], v[12:13], v[204:205]
	v_pk_fma_f32 v[8:9], v[136:137], v[8:9], v[200:201]
	global_load_dwordx4 v[136:139], v[182:183], off offset:528
	global_load_dwordx4 v[140:143], v[182:183], off offset:512
	v_cndmask_b32_e32 v15, v235, v15, vcc
	v_cndmask_b32_e32 v14, v235, v14, vcc
	v_cndmask_b32_e32 v13, v235, v13, vcc
	v_cndmask_b32_e32 v12, v235, v12, vcc
	v_cndmask_b32_e32 v11, v235, v11, vcc
	v_cndmask_b32_e32 v10, v235, v10, vcc
	v_cndmask_b32_e32 v9, v235, v9, vcc
	v_cndmask_b32_e32 v8, v235, v8, vcc
	s_waitcnt vmcnt(1)
	v_pk_fma_f32 v[0:1], v[128:129], v[0:1], v[136:137]
	v_mul_f32_e32 v128, v53, v53
	v_mul_f32_e32 v129, v55, v55
	v_fmac_f32_e32 v128, v52, v52
	v_fmac_f32_e32 v129, v54, v54
	v_pk_fma_f32 v[2:3], v[130:131], v[2:3], v[138:139]
	v_add_f32_e32 v128, v128, v129
	v_mul_f32_e32 v129, v49, v49
	v_mul_f32_e32 v130, v51, v51
	v_fmac_f32_e32 v129, v48, v48
	v_fmac_f32_e32 v130, v50, v50
	v_add_f32_e32 v129, v129, v130
	v_add_f32_e32 v128, v128, v129
	v_mul_f32_e32 v129, v61, v61
	v_mul_f32_e32 v130, v63, v63
	v_fmac_f32_e32 v129, v60, v60
	v_fmac_f32_e32 v130, v62, v62
	v_add_f32_e32 v129, v129, v130
	v_add_f32_e32 v128, v129, v128
	v_mul_f32_e32 v129, v57, v57
	v_mul_f32_e32 v130, v59, v59
	v_fmac_f32_e32 v129, v56, v56
	v_fmac_f32_e32 v130, v58, v58
	v_add_f32_e32 v129, v129, v130
	v_add_f32_e32 v128, v129, v128
	v_mov_b32_e32 v129, v128
	s_nop 1
	v_permlane16_swap_b32 v129, v128
	s_waitcnt vmcnt(0)
	v_pk_fma_f32 v[6:7], v[134:135], v[6:7], v[142:143]
	v_pk_fma_f32 v[4:5], v[132:133], v[4:5], v[140:141]
	v_cndmask_b32_e32 v7, v235, v7, vcc
	v_cndmask_b32_e32 v6, v235, v6, vcc
	s_waitcnt lgkmcnt(0)
	v_add_f32_e32 v128, v128, v129
	v_mov_b32_e32 v129, v128
	s_nop 1
	v_permlane32_swap_b32 v129, v128
	v_cndmask_b32_e32 v5, v235, v5, vcc
	v_cndmask_b32_e32 v4, v235, v4, vcc
	v_cndmask_b32_e32 v3, v235, v3, vcc
	v_cndmask_b32_e32 v2, v235, v2, vcc
	v_cndmask_b32_e32 v1, v235, v1, vcc
	v_cndmask_b32_e32 v0, v235, v0, vcc
	s_and_saveexec_b64 s[14:15], s[6:7]
	s_cbranch_execz .LBB0_1770
	s_lshl_b32 s21, s2, 10
	s_add_i32 s21, s3, s21
	v_lshl_add_u32 v130, v145, 4, s21
	s_waitcnt lgkmcnt(0)
	v_add_f32_e32 v128, v128, v129
	ds_write_b32 v130, v128
.LBB0_1770:
	s_or_b64 exec, exec, s[14:15]
	v_mul_f32_e32 v128, v73, v73
	s_waitcnt lgkmcnt(0)
	v_mul_f32_e32 v129, v75, v75
	v_fmac_f32_e32 v128, v72, v72
	v_fmac_f32_e32 v129, v74, v74
	v_add_f32_e32 v128, v128, v129
	v_mul_f32_e32 v129, v77, v77
	v_mul_f32_e32 v130, v79, v79
	v_fmac_f32_e32 v129, v76, v76
	v_fmac_f32_e32 v130, v78, v78
	v_add_f32_e32 v129, v129, v130
	v_add_f32_e32 v128, v128, v129
	v_mul_f32_e32 v129, v89, v89
	v_mul_f32_e32 v130, v91, v91
	v_fmac_f32_e32 v129, v88, v88
	v_fmac_f32_e32 v130, v90, v90
	v_add_f32_e32 v129, v129, v130
	v_add_f32_e32 v128, v129, v128
	v_mul_f32_e32 v129, v93, v93
	v_mul_f32_e32 v130, v95, v95
	v_fmac_f32_e32 v129, v92, v92
	v_fmac_f32_e32 v130, v94, v94
	v_add_f32_e32 v129, v129, v130
	v_add_f32_e32 v128, v129, v128
	v_mov_b32_e32 v129, v128
	s_nop 1
	v_permlane16_swap_b32 v129, v128
	s_waitcnt lgkmcnt(0)
	v_add_f32_e32 v128, v128, v129
	v_mov_b32_e32 v129, v128
	s_nop 1
	v_permlane32_swap_b32 v129, v128
	s_and_saveexec_b64 s[14:15], s[6:7]
	s_cbranch_execz .LBB0_1772
	s_lshl_b32 s21, s2, 10
	s_add_i32 s21, s3, s21
	v_lshl_add_u32 v130, v145, 4, s21
	s_waitcnt lgkmcnt(0)
	v_add_f32_e32 v128, v128, v129
	ds_write_b32 v130, v128 offset:256
.LBB0_1772:
	s_or_b64 exec, exec, s[14:15]
	v_mul_f32_e32 v128, v105, v105
	s_waitcnt lgkmcnt(0)
	v_mul_f32_e32 v129, v107, v107
	v_fmac_f32_e32 v128, v104, v104
	v_fmac_f32_e32 v129, v106, v106
	v_add_f32_e32 v128, v128, v129
	v_mul_f32_e32 v129, v101, v101
	v_mul_f32_e32 v130, v103, v103
	v_fmac_f32_e32 v129, v100, v100
	v_fmac_f32_e32 v130, v102, v102
	v_add_f32_e32 v129, v129, v130
	v_add_f32_e32 v128, v128, v129
	v_mul_f32_e32 v129, v117, v117
	v_mul_f32_e32 v130, v119, v119
	v_fmac_f32_e32 v129, v116, v116
	v_fmac_f32_e32 v130, v118, v118
	v_add_f32_e32 v129, v129, v130
	v_add_f32_e32 v128, v129, v128
	v_mul_f32_e32 v129, v113, v113
	v_mul_f32_e32 v130, v115, v115
	v_fmac_f32_e32 v129, v112, v112
	v_fmac_f32_e32 v130, v114, v114
	v_add_f32_e32 v129, v129, v130
	v_add_f32_e32 v128, v129, v128
	v_mov_b32_e32 v129, v128
	s_nop 1
	v_permlane16_swap_b32 v129, v128
	s_waitcnt lgkmcnt(0)
	v_add_f32_e32 v128, v128, v129
	v_mov_b32_e32 v129, v128
	s_nop 1
	v_permlane32_swap_b32 v129, v128
	s_and_saveexec_b64 s[14:15], s[6:7]
	s_cbranch_execz .LBB0_1774
	s_lshl_b32 s21, s2, 10
	s_add_i32 s21, s3, s21
	v_lshl_add_u32 v130, v145, 4, s21
	s_waitcnt lgkmcnt(0)
	v_add_f32_e32 v128, v128, v129
	ds_write_b32 v130, v128 offset:512
.LBB0_1774:
	s_or_b64 exec, exec, s[14:15]
	v_mul_f32_e32 v128, v125, v125
	s_waitcnt lgkmcnt(0)
	v_mul_f32_e32 v129, v127, v127
	v_fmac_f32_e32 v128, v124, v124
	v_fmac_f32_e32 v129, v126, v126
	v_add_f32_e32 v128, v128, v129
	v_mul_f32_e32 v129, v121, v121
	v_mul_f32_e32 v130, v123, v123
	v_fmac_f32_e32 v129, v120, v120
	v_fmac_f32_e32 v130, v122, v122
	v_add_f32_e32 v129, v129, v130
	v_add_f32_e32 v128, v128, v129
	v_mul_f32_e32 v129, v109, v109
	v_mul_f32_e32 v130, v111, v111
	v_fmac_f32_e32 v129, v108, v108
	v_fmac_f32_e32 v130, v110, v110
	v_add_f32_e32 v129, v129, v130
	v_add_f32_e32 v128, v129, v128
	v_mul_f32_e32 v129, v97, v97
	v_mul_f32_e32 v130, v99, v99
	v_fmac_f32_e32 v129, v96, v96
	v_fmac_f32_e32 v130, v98, v98
	v_add_f32_e32 v129, v129, v130
	v_add_f32_e32 v128, v129, v128
	v_mov_b32_e32 v129, v128
	s_nop 1
	v_permlane16_swap_b32 v129, v128
	s_waitcnt lgkmcnt(0)
	v_add_f32_e32 v128, v128, v129
	v_mov_b32_e32 v129, v128
	s_nop 1
	v_permlane32_swap_b32 v129, v128
	s_and_saveexec_b64 s[14:15], s[6:7]
	s_cbranch_execz .LBB0_1776
	s_lshl_b32 s21, s2, 10
	s_add_i32 s21, s3, s21
	v_lshl_add_u32 v130, v145, 4, s21
	s_waitcnt lgkmcnt(0)
	v_add_f32_e32 v128, v128, v129
	ds_write_b32 v130, v128 offset:768
.LBB0_1776:
	s_or_b64 exec, exec, s[14:15]
	v_mul_f32_e32 v128, v85, v85
	s_waitcnt lgkmcnt(0)
	v_mul_f32_e32 v129, v87, v87
	v_fmac_f32_e32 v128, v84, v84
	v_fmac_f32_e32 v129, v86, v86
	v_add_f32_e32 v128, v128, v129
	v_mul_f32_e32 v129, v81, v81
	v_mul_f32_e32 v130, v83, v83
	v_fmac_f32_e32 v129, v80, v80
	v_fmac_f32_e32 v130, v82, v82
	v_add_f32_e32 v129, v129, v130
	v_add_f32_e32 v128, v128, v129
	v_mul_f32_e32 v129, v69, v69
	v_mul_f32_e32 v130, v71, v71
	v_fmac_f32_e32 v129, v68, v68
	v_fmac_f32_e32 v130, v70, v70
	v_add_f32_e32 v129, v129, v130
	v_add_f32_e32 v128, v129, v128
	v_mul_f32_e32 v129, v65, v65
	v_mul_f32_e32 v130, v67, v67
	v_fmac_f32_e32 v129, v64, v64
	v_fmac_f32_e32 v130, v66, v66
	v_add_f32_e32 v129, v129, v130
	v_add_f32_e32 v128, v129, v128
	v_mov_b32_e32 v129, v128
	s_nop 1
	v_permlane16_swap_b32 v129, v128
	s_waitcnt lgkmcnt(0)
	v_add_f32_e32 v128, v128, v129
	v_mov_b32_e32 v129, v128
	s_nop 1
	v_permlane32_swap_b32 v129, v128
	s_and_saveexec_b64 s[14:15], s[6:7]
	s_cbranch_execz .LBB0_1778
	s_lshl_b32 s21, s2, 10
	s_add_i32 s21, s3, s21
	v_lshl_add_u32 v130, v145, 4, s21
	s_waitcnt lgkmcnt(0)
	v_add_f32_e32 v128, v128, v129
	ds_write_b32 v130, v128 offset:2048
.LBB0_1778:
	s_or_b64 exec, exec, s[14:15]
	v_mul_f32_e32 v128, v45, v45
	s_waitcnt lgkmcnt(0)
	v_mul_f32_e32 v129, v47, v47
	v_fmac_f32_e32 v128, v44, v44
	v_fmac_f32_e32 v129, v46, v46
	v_add_f32_e32 v128, v128, v129
	v_mul_f32_e32 v129, v41, v41
	v_mul_f32_e32 v130, v43, v43
	v_fmac_f32_e32 v129, v40, v40
	v_fmac_f32_e32 v130, v42, v42
	v_add_f32_e32 v129, v129, v130
	v_add_f32_e32 v128, v128, v129
	v_mul_f32_e32 v129, v37, v37
	v_mul_f32_e32 v130, v39, v39
	v_fmac_f32_e32 v129, v36, v36
	v_fmac_f32_e32 v130, v38, v38
	v_add_f32_e32 v129, v129, v130
	v_add_f32_e32 v128, v129, v128
	v_mul_f32_e32 v129, v33, v33
	v_mul_f32_e32 v130, v35, v35
	v_fmac_f32_e32 v129, v32, v32
	v_fmac_f32_e32 v130, v34, v34
	v_add_f32_e32 v129, v129, v130
	v_add_f32_e32 v128, v129, v128
	v_mov_b32_e32 v129, v128
	s_nop 1
	v_permlane16_swap_b32 v129, v128
	s_waitcnt lgkmcnt(0)
	v_add_f32_e32 v128, v128, v129
	v_mov_b32_e32 v129, v128
	s_nop 1
	v_permlane32_swap_b32 v129, v128
	s_and_saveexec_b64 s[14:15], s[6:7]
	s_cbranch_execz .LBB0_1780
	s_lshl_b32 s21, s2, 10
	s_add_i32 s21, s3, s21
	v_lshl_add_u32 v130, v145, 4, s21
	s_waitcnt lgkmcnt(0)
	v_add_f32_e32 v128, v128, v129
	ds_write_b32 v130, v128 offset:2304
.LBB0_1780:
	s_or_b64 exec, exec, s[14:15]
	v_mul_f32_e32 v128, v29, v29
	s_waitcnt lgkmcnt(0)
	v_mul_f32_e32 v129, v31, v31
	v_fmac_f32_e32 v128, v28, v28
	v_fmac_f32_e32 v129, v30, v30
	v_add_f32_e32 v128, v128, v129
	v_mul_f32_e32 v129, v25, v25
	v_mul_f32_e32 v130, v27, v27
	v_fmac_f32_e32 v129, v24, v24
	v_fmac_f32_e32 v130, v26, v26
	v_add_f32_e32 v129, v129, v130
	v_add_f32_e32 v128, v128, v129
	v_mul_f32_e32 v129, v21, v21
	v_mul_f32_e32 v130, v23, v23
	v_fmac_f32_e32 v129, v20, v20
	v_fmac_f32_e32 v130, v22, v22
	v_add_f32_e32 v129, v129, v130
	v_add_f32_e32 v128, v129, v128
	v_mul_f32_e32 v129, v17, v17
	v_mul_f32_e32 v130, v19, v19
	v_fmac_f32_e32 v129, v16, v16
	v_fmac_f32_e32 v130, v18, v18
	v_add_f32_e32 v129, v129, v130
	v_add_f32_e32 v128, v129, v128
	v_mov_b32_e32 v129, v128
	s_nop 1
	v_permlane16_swap_b32 v129, v128
	s_waitcnt lgkmcnt(0)
	v_add_f32_e32 v128, v128, v129
	v_mov_b32_e32 v129, v128
	s_nop 1
	v_permlane32_swap_b32 v129, v128
	s_and_saveexec_b64 s[14:15], s[6:7]
	s_cbranch_execz .LBB0_1782
	s_lshl_b32 s21, s2, 10
	s_add_i32 s21, s3, s21
	v_lshl_add_u32 v130, v145, 4, s21
	s_waitcnt lgkmcnt(0)
	v_add_f32_e32 v128, v128, v129
	ds_write_b32 v130, v128 offset:2560
.LBB0_1782:
	s_or_b64 exec, exec, s[14:15]
	v_mul_f32_e32 v128, v13, v13
	s_waitcnt lgkmcnt(0)
	v_mul_f32_e32 v129, v15, v15
	v_fmac_f32_e32 v128, v12, v12
	v_fmac_f32_e32 v129, v14, v14
	v_add_f32_e32 v128, v128, v129
	v_mul_f32_e32 v129, v9, v9
	v_mul_f32_e32 v130, v11, v11
	v_fmac_f32_e32 v129, v8, v8
	v_fmac_f32_e32 v130, v10, v10
	v_add_f32_e32 v129, v129, v130
	v_add_f32_e32 v128, v128, v129
	v_mul_f32_e32 v129, v5, v5
	v_mul_f32_e32 v130, v7, v7
	v_fmac_f32_e32 v129, v4, v4
	v_fmac_f32_e32 v130, v6, v6
	v_add_f32_e32 v129, v129, v130
	v_add_f32_e32 v128, v129, v128
	v_mul_f32_e32 v129, v1, v1
	v_mul_f32_e32 v130, v3, v3
	v_fmac_f32_e32 v129, v0, v0
	v_fmac_f32_e32 v130, v2, v2
	v_add_f32_e32 v129, v129, v130
	v_add_f32_e32 v128, v129, v128
	v_mov_b32_e32 v129, v128
	s_nop 1
	v_permlane16_swap_b32 v129, v128
	s_waitcnt lgkmcnt(0)
	v_add_f32_e32 v128, v128, v129
	v_mov_b32_e32 v129, v128
	s_nop 1
	v_permlane32_swap_b32 v129, v128
	s_and_saveexec_b64 s[14:15], s[6:7]
	s_cbranch_execz .LBB0_1784
	s_lshl_b32 s2, s2, 10
	s_add_i32 s3, s3, s2
	v_lshl_add_u32 v130, v145, 4, s3
	s_waitcnt lgkmcnt(0)
	v_add_f32_e32 v128, v128, v129
	ds_write_b32 v130, v128 offset:2816

.LBB0_2167:
	v_and_b32_e32 v130, 64, v228
	v_xor_b32_e32 v129, 16, v228
	v_add_u32_e32 v130, 64, v130
	v_cmp_lt_i32_e32 vcc, v129, v130
	v_mul_f32_e32 v131, v123, v123
	v_fmac_f32_e32 v131, v122, v122
	v_cndmask_b32_e32 v129, v228, v129, vcc
	v_lshlrev_b32_e32 v160, 2, v129
	v_mul_f32_e32 v129, v121, v121
	v_fmac_f32_e32 v129, v120, v120
	v_add_f32_e32 v129, v129, v131
	v_mul_f32_e32 v131, v125, v125
	v_mul_f32_e32 v132, v127, v127
	v_fmac_f32_e32 v131, v124, v124
	v_fmac_f32_e32 v132, v126, v126
	v_add_f32_e32 v131, v131, v132
	v_add_f32_e32 v129, v131, v129
	v_mul_f32_e32 v131, v117, v117
	v_mul_f32_e32 v132, v119, v119
	v_fmac_f32_e32 v131, v116, v116
	v_fmac_f32_e32 v132, v118, v118
	v_add_f32_e32 v131, v131, v132
	v_add_f32_e32 v129, v131, v129
	v_mul_f32_e32 v131, v113, v113
	v_mul_f32_e32 v132, v115, v115
	v_fmac_f32_e32 v131, v112, v112
	v_fmac_f32_e32 v132, v114, v114
	v_add_f32_e32 v131, v131, v132
	v_add_f32_e32 v129, v131, v129
	v_mov_b32_e32 v131, v129
	s_nop 1
	v_permlane16_swap_b32 v131, v129
	v_xor_b32_e32 v132, 32, v228
	v_cmp_lt_i32_e32 vcc, v132, v130
	v_and_b32_e32 v128, 63, v142
	s_lshl_b32 s3, s33, 2
	v_cndmask_b32_e32 v130, v228, v132, vcc
	v_lshlrev_b32_e32 v197, 2, v130
	s_waitcnt lgkmcnt(0)
	v_add_f32_e32 v129, v129, v131
	v_mov_b32_e32 v130, v129
	s_nop 1
	v_permlane32_swap_b32 v130, v129
	v_cmp_gt_u32_e64 s[4:5], 16, v128
	s_add_i32 s3, s3, 0
	s_barrier
	s_and_saveexec_b64 s[6:7], s[4:5]
	s_cbranch_execz .LBB0_2169
	s_lshl_b32 s8, s2, 10
	s_add_i32 s8, s3, s8
	v_lshl_add_u32 v131, v195, 4, s8
	s_waitcnt lgkmcnt(0)
	v_add_f32_e32 v129, v129, v130
	ds_write_b32 v131, v129
.LBB0_2169:
	s_or_b64 exec, exec, s[6:7]
	v_mul_f32_e32 v129, v109, v109
	s_waitcnt lgkmcnt(0)
	v_mul_f32_e32 v130, v111, v111
	v_fmac_f32_e32 v129, v108, v108
	v_fmac_f32_e32 v130, v110, v110
	v_add_f32_e32 v129, v129, v130
	v_mul_f32_e32 v130, v105, v105
	v_mul_f32_e32 v131, v107, v107
	v_fmac_f32_e32 v130, v104, v104
	v_fmac_f32_e32 v131, v106, v106
	v_add_f32_e32 v130, v130, v131
	v_add_f32_e32 v129, v130, v129
	v_mul_f32_e32 v130, v101, v101
	v_mul_f32_e32 v131, v103, v103
	v_fmac_f32_e32 v130, v100, v100
	v_fmac_f32_e32 v131, v102, v102
	v_add_f32_e32 v130, v130, v131
	v_add_f32_e32 v129, v130, v129
	v_mul_f32_e32 v130, v97, v97
	v_mul_f32_e32 v131, v99, v99
	v_fmac_f32_e32 v130, v96, v96
	v_fmac_f32_e32 v131, v98, v98
	v_add_f32_e32 v130, v130, v131
	v_add_f32_e32 v129, v130, v129
	v_mov_b32_e32 v130, v129
	s_nop 1
	v_permlane16_swap_b32 v130, v129
	s_waitcnt lgkmcnt(0)
	v_add_f32_e32 v129, v129, v130
	v_mov_b32_e32 v130, v129
	s_nop 1
	v_permlane32_swap_b32 v130, v129
	s_and_saveexec_b64 s[6:7], s[4:5]
	s_cbranch_execz .LBB0_2171
	s_lshl_b32 s8, s2, 10
	s_add_i32 s8, s3, s8
	v_lshl_add_u32 v131, v195, 4, s8
	s_waitcnt lgkmcnt(0)
	v_add_f32_e32 v129, v129, v130
	ds_write_b32 v131, v129 offset:256
.LBB0_2171:
	s_or_b64 exec, exec, s[6:7]
	v_mul_f32_e32 v129, v93, v93
	s_waitcnt lgkmcnt(0)
	v_mul_f32_e32 v130, v95, v95
	v_fmac_f32_e32 v129, v92, v92
	v_fmac_f32_e32 v130, v94, v94
	v_add_f32_e32 v129, v129, v130
	v_mul_f32_e32 v130, v89, v89
	v_mul_f32_e32 v131, v91, v91
	v_fmac_f32_e32 v130, v88, v88
	v_fmac_f32_e32 v131, v90, v90
	v_add_f32_e32 v130, v130, v131
	v_add_f32_e32 v129, v130, v129
	v_mul_f32_e32 v130, v85, v85
	v_mul_f32_e32 v131, v87, v87
	v_fmac_f32_e32 v130, v84, v84
	v_fmac_f32_e32 v131, v86, v86
	v_add_f32_e32 v130, v130, v131
	v_add_f32_e32 v129, v130, v129
	v_mul_f32_e32 v130, v81, v81
	v_mul_f32_e32 v131, v83, v83
	v_fmac_f32_e32 v130, v80, v80
	v_fmac_f32_e32 v131, v82, v82
	v_add_f32_e32 v130, v130, v131
	v_add_f32_e32 v129, v130, v129
	v_mov_b32_e32 v130, v129
	s_nop 1
	v_permlane16_swap_b32 v130, v129
	s_waitcnt lgkmcnt(0)
	v_add_f32_e32 v129, v129, v130
	v_mov_b32_e32 v130, v129
	s_nop 1
	v_permlane32_swap_b32 v130, v129
	s_and_saveexec_b64 s[6:7], s[4:5]
	s_cbranch_execz .LBB0_2173
	s_lshl_b32 s8, s2, 10
	s_add_i32 s8, s3, s8
	v_lshl_add_u32 v131, v195, 4, s8
	s_waitcnt lgkmcnt(0)
	v_add_f32_e32 v129, v129, v130
	ds_write_b32 v131, v129 offset:512
.LBB0_2173:
	s_or_b64 exec, exec, s[6:7]
	v_mul_f32_e32 v129, v77, v77
	s_waitcnt lgkmcnt(0)
	v_mul_f32_e32 v130, v79, v79
	v_fmac_f32_e32 v129, v76, v76
	v_fmac_f32_e32 v130, v78, v78
	v_add_f32_e32 v129, v129, v130
	v_mul_f32_e32 v130, v73, v73
	v_mul_f32_e32 v131, v75, v75
	v_fmac_f32_e32 v130, v72, v72
	v_fmac_f32_e32 v131, v74, v74
	v_add_f32_e32 v130, v130, v131
	v_add_f32_e32 v129, v130, v129
	v_mul_f32_e32 v130, v69, v69
	v_mul_f32_e32 v131, v71, v71
	v_fmac_f32_e32 v130, v68, v68
	v_fmac_f32_e32 v131, v70, v70
	v_add_f32_e32 v130, v130, v131
	v_add_f32_e32 v129, v130, v129
	v_mul_f32_e32 v130, v65, v65
	v_mul_f32_e32 v131, v67, v67
	v_fmac_f32_e32 v130, v64, v64
	v_fmac_f32_e32 v131, v66, v66
	v_add_f32_e32 v130, v130, v131
	v_add_f32_e32 v129, v130, v129
	v_mov_b32_e32 v130, v129
	s_nop 1
	v_permlane16_swap_b32 v130, v129
	s_waitcnt lgkmcnt(0)
	v_add_f32_e32 v129, v129, v130
	v_mov_b32_e32 v130, v129
	s_nop 1
	v_permlane32_swap_b32 v130, v129
	s_and_saveexec_b64 s[6:7], s[4:5]
	s_cbranch_execz .LBB0_2175
	s_lshl_b32 s8, s2, 10
	s_add_i32 s8, s3, s8
	v_lshl_add_u32 v131, v195, 4, s8
	s_waitcnt lgkmcnt(0)
	v_add_f32_e32 v129, v129, v130
	ds_write_b32 v131, v129 offset:768
.LBB0_2175:
	s_or_b64 exec, exec, s[6:7]
	v_mul_f32_e32 v129, v61, v61
	s_waitcnt lgkmcnt(0)
	v_mul_f32_e32 v130, v63, v63
	v_fmac_f32_e32 v129, v60, v60
	v_fmac_f32_e32 v130, v62, v62
	v_add_f32_e32 v129, v129, v130
	v_mul_f32_e32 v130, v57, v57
	v_mul_f32_e32 v131, v59, v59
	v_fmac_f32_e32 v130, v56, v56
	v_fmac_f32_e32 v131, v58, v58
	v_add_f32_e32 v130, v130, v131
	v_add_f32_e32 v129, v130, v129
	v_mul_f32_e32 v130, v53, v53
	v_mul_f32_e32 v131, v55, v55
	v_fmac_f32_e32 v130, v52, v52
	v_fmac_f32_e32 v131, v54, v54
	v_add_f32_e32 v130, v130, v131
	v_add_f32_e32 v129, v130, v129
	v_mul_f32_e32 v130, v49, v49
	v_mul_f32_e32 v131, v51, v51
	v_fmac_f32_e32 v130, v48, v48
	v_fmac_f32_e32 v131, v50, v50
	v_add_f32_e32 v130, v130, v131
	v_add_f32_e32 v129, v130, v129
	v_mov_b32_e32 v130, v129
	s_nop 1
	v_permlane16_swap_b32 v130, v129
	s_waitcnt lgkmcnt(0)
	v_add_f32_e32 v129, v129, v130
	v_mov_b32_e32 v130, v129
	s_nop 1
	v_permlane32_swap_b32 v130, v129
	s_and_saveexec_b64 s[6:7], s[4:5]
	s_cbranch_execz .LBB0_2177
	s_lshl_b32 s8, s2, 10
	s_add_i32 s8, s3, s8
	v_lshl_add_u32 v131, v195, 4, s8
	s_waitcnt lgkmcnt(0)
	v_add_f32_e32 v129, v129, v130
	ds_write_b32 v131, v129 offset:2048
.LBB0_2177:
	s_or_b64 exec, exec, s[6:7]
	v_mul_f32_e32 v129, v45, v45
	s_waitcnt lgkmcnt(0)
	v_mul_f32_e32 v130, v47, v47
	v_fmac_f32_e32 v129, v44, v44
	v_fmac_f32_e32 v130, v46, v46
	v_add_f32_e32 v129, v129, v130
	v_mul_f32_e32 v130, v41, v41
	v_mul_f32_e32 v131, v43, v43
	v_fmac_f32_e32 v130, v40, v40
	v_fmac_f32_e32 v131, v42, v42
	v_add_f32_e32 v130, v130, v131
	v_add_f32_e32 v129, v130, v129
	v_mul_f32_e32 v130, v37, v37
	v_mul_f32_e32 v131, v39, v39
	v_fmac_f32_e32 v130, v36, v36
	v_fmac_f32_e32 v131, v38, v38
	v_add_f32_e32 v130, v130, v131
	v_add_f32_e32 v129, v130, v129
	v_mul_f32_e32 v130, v33, v33
	v_mul_f32_e32 v131, v35, v35
	v_fmac_f32_e32 v130, v32, v32
	v_fmac_f32_e32 v131, v34, v34
	v_add_f32_e32 v130, v130, v131
	v_add_f32_e32 v129, v130, v129
	v_mov_b32_e32 v130, v129
	s_nop 1
	v_permlane16_swap_b32 v130, v129
	s_waitcnt lgkmcnt(0)
	v_add_f32_e32 v129, v129, v130
	v_mov_b32_e32 v130, v129
	s_nop 1
	v_permlane32_swap_b32 v130, v129
	s_and_saveexec_b64 s[6:7], s[4:5]
	s_cbranch_execz .LBB0_2179
	s_lshl_b32 s8, s2, 10
	s_add_i32 s8, s3, s8
	v_lshl_add_u32 v131, v195, 4, s8
	s_waitcnt lgkmcnt(0)
	v_add_f32_e32 v129, v129, v130
	ds_write_b32 v131, v129 offset:2304
.LBB0_2179:
	s_or_b64 exec, exec, s[6:7]
	v_mul_f32_e32 v129, v29, v29
	s_waitcnt lgkmcnt(0)
	v_mul_f32_e32 v130, v31, v31
	v_fmac_f32_e32 v129, v28, v28
	v_fmac_f32_e32 v130, v30, v30
	v_add_f32_e32 v129, v129, v130
	v_mul_f32_e32 v130, v25, v25
	v_mul_f32_e32 v131, v27, v27
	v_fmac_f32_e32 v130, v24, v24
	v_fmac_f32_e32 v131, v26, v26
	v_add_f32_e32 v130, v130, v131
	v_add_f32_e32 v129, v130, v129
	v_mul_f32_e32 v130, v21, v21
	v_mul_f32_e32 v131, v23, v23
	v_fmac_f32_e32 v130, v20, v20
	v_fmac_f32_e32 v131, v22, v22
	v_add_f32_e32 v130, v130, v131
	v_add_f32_e32 v129, v130, v129
	v_mul_f32_e32 v130, v17, v17
	v_mul_f32_e32 v131, v19, v19
	v_fmac_f32_e32 v130, v16, v16
	v_fmac_f32_e32 v131, v18, v18
	v_add_f32_e32 v130, v130, v131
	v_add_f32_e32 v129, v130, v129
	v_mov_b32_e32 v130, v129
	s_nop 1
	v_permlane16_swap_b32 v130, v129
	s_waitcnt lgkmcnt(0)
	v_add_f32_e32 v129, v129, v130
	v_mov_b32_e32 v130, v129
	s_nop 1
	v_permlane32_swap_b32 v130, v129
	s_and_saveexec_b64 s[6:7], s[4:5]
	s_cbranch_execz .LBB0_2181
	s_lshl_b32 s8, s2, 10
	s_add_i32 s8, s3, s8
	v_lshl_add_u32 v131, v195, 4, s8
	s_waitcnt lgkmcnt(0)
	v_add_f32_e32 v129, v129, v130
	ds_write_b32 v131, v129 offset:2560
.LBB0_2181:
	s_or_b64 exec, exec, s[6:7]
	v_mul_f32_e32 v129, v13, v13
	s_waitcnt lgkmcnt(0)
	v_mul_f32_e32 v130, v15, v15
	v_fmac_f32_e32 v129, v12, v12
	v_fmac_f32_e32 v130, v14, v14
	v_add_f32_e32 v129, v129, v130
	v_mul_f32_e32 v130, v9, v9
	v_mul_f32_e32 v131, v11, v11
	v_fmac_f32_e32 v130, v8, v8
	v_fmac_f32_e32 v131, v10, v10
	v_add_f32_e32 v130, v130, v131
	v_add_f32_e32 v129, v130, v129
	v_mul_f32_e32 v130, v5, v5
	v_mul_f32_e32 v131, v7, v7
	v_fmac_f32_e32 v130, v4, v4
	v_fmac_f32_e32 v131, v6, v6
	v_add_f32_e32 v130, v130, v131
	v_add_f32_e32 v129, v130, v129
	v_mul_f32_e32 v130, v1, v1
	v_mul_f32_e32 v131, v3, v3
	v_fmac_f32_e32 v130, v0, v0
	v_fmac_f32_e32 v131, v2, v2
	v_add_f32_e32 v130, v130, v131
	v_add_f32_e32 v129, v130, v129
	v_mov_b32_e32 v130, v129
	s_nop 1
	v_permlane16_swap_b32 v130, v129
	s_waitcnt lgkmcnt(0)
	v_add_f32_e32 v129, v129, v130
	v_mov_b32_e32 v130, v129
	s_nop 1
	v_permlane32_swap_b32 v130, v129
	s_and_saveexec_b64 s[6:7], s[4:5]
	s_cbranch_execz .LBB0_2183
	s_lshl_b32 s8, s2, 10
	s_add_i32 s8, s3, s8
	v_lshl_add_u32 v131, v195, 4, s8
	s_waitcnt lgkmcnt(0)
	v_add_f32_e32 v129, v129, v130
	ds_write_b32 v131, v129 offset:2816

.LBB0_2276:
	s_nop 1
	v_readlane_b32 s12, v255, 53
	v_readlane_b32 s13, v255, 54
	s_andn2_b64 vcc, exec, s[12:13]
	s_cbranch_vccnz .LBB0_2339
	v_mul_f32_e32 v128, v121, v121
	v_mul_f32_e32 v129, v123, v123
	v_fmac_f32_e32 v128, v120, v120
	v_fmac_f32_e32 v129, v122, v122
	v_add_f32_e32 v128, v128, v129
	v_mul_f32_e32 v129, v125, v125
	v_mul_f32_e32 v130, v127, v127
	v_fmac_f32_e32 v129, v124, v124
	v_fmac_f32_e32 v130, v126, v126
	v_add_f32_e32 v129, v129, v130
	v_add_f32_e32 v128, v128, v129
	v_mul_f32_e32 v129, v117, v117
	v_mul_f32_e32 v130, v119, v119
	v_fmac_f32_e32 v129, v116, v116
	v_fmac_f32_e32 v130, v118, v118
	v_add_f32_e32 v129, v129, v130
	v_add_f32_e32 v128, v129, v128
	v_mul_f32_e32 v129, v113, v113
	v_mul_f32_e32 v130, v115, v115
	v_fmac_f32_e32 v129, v112, v112
	v_fmac_f32_e32 v130, v114, v114
	v_add_f32_e32 v129, v129, v130
	v_add_f32_e32 v128, v129, v128
	v_mov_b32_e32 v129, v128
	s_nop 1
	v_permlane16_swap_b32 v129, v128
	s_waitcnt lgkmcnt(0)
	v_add_f32_e32 v128, v128, v129
	v_mov_b32_e32 v129, v128
	s_nop 1
	v_permlane32_swap_b32 v129, v128
	s_and_saveexec_b64 s[12:13], s[4:5]
	s_cbranch_execz .LBB0_2279
	s_lshl_b32 s14, s2, 10
	s_add_i32 s14, s3, s14
	v_lshl_add_u32 v130, v195, 4, s14
	s_waitcnt lgkmcnt(0)
	v_add_f32_e32 v128, v128, v129
	ds_write_b32 v130, v128
.LBB0_2279:
	s_or_b64 exec, exec, s[12:13]
	v_mul_f32_e32 v128, v109, v109
	s_waitcnt lgkmcnt(0)
	v_mul_f32_e32 v129, v111, v111
	v_fmac_f32_e32 v128, v108, v108
	v_fmac_f32_e32 v129, v110, v110
	v_add_f32_e32 v128, v128, v129
	v_mul_f32_e32 v129, v105, v105
	v_mul_f32_e32 v130, v107, v107
	v_fmac_f32_e32 v129, v104, v104
	v_fmac_f32_e32 v130, v106, v106
	v_add_f32_e32 v129, v129, v130
	v_add_f32_e32 v128, v128, v129
	v_mul_f32_e32 v129, v101, v101
	v_mul_f32_e32 v130, v103, v103
	v_fmac_f32_e32 v129, v100, v100
	v_fmac_f32_e32 v130, v102, v102
	v_add_f32_e32 v129, v129, v130
	v_add_f32_e32 v128, v129, v128
	v_mul_f32_e32 v129, v97, v97
	v_mul_f32_e32 v130, v99, v99
	v_fmac_f32_e32 v129, v96, v96
	v_fmac_f32_e32 v130, v98, v98
	v_add_f32_e32 v129, v129, v130
	v_add_f32_e32 v128, v129, v128
	v_mov_b32_e32 v129, v128
	s_nop 1
	v_permlane16_swap_b32 v129, v128
	s_waitcnt lgkmcnt(0)
	v_add_f32_e32 v128, v128, v129
	v_mov_b32_e32 v129, v128
	s_nop 1
	v_permlane32_swap_b32 v129, v128
	s_and_saveexec_b64 s[12:13], s[4:5]
	s_cbranch_execz .LBB0_2281
	s_lshl_b32 s14, s2, 10
	s_add_i32 s14, s3, s14
	v_lshl_add_u32 v130, v195, 4, s14
	s_waitcnt lgkmcnt(0)
	v_add_f32_e32 v128, v128, v129
	ds_write_b32 v130, v128 offset:256
.LBB0_2281:
	s_or_b64 exec, exec, s[12:13]
	v_mul_f32_e32 v128, v93, v93
	s_waitcnt lgkmcnt(0)
	v_mul_f32_e32 v129, v95, v95
	v_fmac_f32_e32 v128, v92, v92
	v_fmac_f32_e32 v129, v94, v94
	v_add_f32_e32 v128, v128, v129
	v_mul_f32_e32 v129, v89, v89
	v_mul_f32_e32 v130, v91, v91
	v_fmac_f32_e32 v129, v88, v88
	v_fmac_f32_e32 v130, v90, v90
	v_add_f32_e32 v129, v129, v130
	v_add_f32_e32 v128, v128, v129
	v_mul_f32_e32 v129, v85, v85
	v_mul_f32_e32 v130, v87, v87
	v_fmac_f32_e32 v129, v84, v84
	v_fmac_f32_e32 v130, v86, v86
	v_add_f32_e32 v129, v129, v130
	v_add_f32_e32 v128, v129, v128
	v_mul_f32_e32 v129, v81, v81
	v_mul_f32_e32 v130, v83, v83
	v_fmac_f32_e32 v129, v80, v80
	v_fmac_f32_e32 v130, v82, v82
	v_add_f32_e32 v129, v129, v130
	v_add_f32_e32 v128, v129, v128
	v_mov_b32_e32 v129, v128
	s_nop 1
	v_permlane16_swap_b32 v129, v128
	s_waitcnt lgkmcnt(0)
	v_add_f32_e32 v128, v128, v129
	v_mov_b32_e32 v129, v128
	s_nop 1
	v_permlane32_swap_b32 v129, v128
	s_and_saveexec_b64 s[12:13], s[4:5]
	s_cbranch_execz .LBB0_2283
	s_lshl_b32 s14, s2, 10
	s_add_i32 s14, s3, s14
	v_lshl_add_u32 v130, v195, 4, s14
	s_waitcnt lgkmcnt(0)
	v_add_f32_e32 v128, v128, v129
	ds_write_b32 v130, v128 offset:512
.LBB0_2283:
	s_or_b64 exec, exec, s[12:13]
	v_mul_f32_e32 v128, v77, v77
	s_waitcnt lgkmcnt(0)
	v_mul_f32_e32 v129, v79, v79
	v_fmac_f32_e32 v128, v76, v76
	v_fmac_f32_e32 v129, v78, v78
	v_add_f32_e32 v128, v128, v129
	v_mul_f32_e32 v129, v73, v73
	v_mul_f32_e32 v130, v75, v75
	v_fmac_f32_e32 v129, v72, v72
	v_fmac_f32_e32 v130, v74, v74
	v_add_f32_e32 v129, v129, v130
	v_add_f32_e32 v128, v128, v129
	v_mul_f32_e32 v129, v69, v69
	v_mul_f32_e32 v130, v71, v71
	v_fmac_f32_e32 v129, v68, v68
	v_fmac_f32_e32 v130, v70, v70
	v_add_f32_e32 v129, v129, v130
	v_add_f32_e32 v128, v129, v128
	v_mul_f32_e32 v129, v65, v65
	v_mul_f32_e32 v130, v67, v67
	v_fmac_f32_e32 v129, v64, v64
	v_fmac_f32_e32 v130, v66, v66
	v_add_f32_e32 v129, v129, v130
	v_add_f32_e32 v128, v129, v128
	v_mov_b32_e32 v129, v128
	s_nop 1
	v_permlane16_swap_b32 v129, v128
	s_waitcnt lgkmcnt(0)
	v_add_f32_e32 v128, v128, v129
	v_mov_b32_e32 v129, v128
	s_nop 1
	v_permlane32_swap_b32 v129, v128
	s_and_saveexec_b64 s[12:13], s[4:5]
	s_cbranch_execz .LBB0_2285
	s_lshl_b32 s14, s2, 10
	s_add_i32 s14, s3, s14
	v_lshl_add_u32 v130, v195, 4, s14
	s_waitcnt lgkmcnt(0)
	v_add_f32_e32 v128, v128, v129
	ds_write_b32 v130, v128 offset:768
.LBB0_2285:
	s_or_b64 exec, exec, s[12:13]
	v_mul_f32_e32 v128, v61, v61
	s_waitcnt lgkmcnt(0)
	v_mul_f32_e32 v129, v63, v63
	v_fmac_f32_e32 v128, v60, v60
	v_fmac_f32_e32 v129, v62, v62
	v_add_f32_e32 v128, v128, v129
	v_mul_f32_e32 v129, v57, v57
	v_mul_f32_e32 v130, v59, v59
	v_fmac_f32_e32 v129, v56, v56
	v_fmac_f32_e32 v130, v58, v58
	v_add_f32_e32 v129, v129, v130
	v_add_f32_e32 v128, v128, v129
	v_mul_f32_e32 v129, v53, v53
	v_mul_f32_e32 v130, v55, v55
	v_fmac_f32_e32 v129, v52, v52
	v_fmac_f32_e32 v130, v54, v54
	v_add_f32_e32 v129, v129, v130
	v_add_f32_e32 v128, v129, v128
	v_mul_f32_e32 v129, v49, v49
	v_mul_f32_e32 v130, v51, v51
	v_fmac_f32_e32 v129, v48, v48
	v_fmac_f32_e32 v130, v50, v50
	v_add_f32_e32 v129, v129, v130
	v_add_f32_e32 v128, v129, v128
	v_mov_b32_e32 v129, v128
	s_nop 1
	v_permlane16_swap_b32 v129, v128
	s_waitcnt lgkmcnt(0)
	v_add_f32_e32 v128, v128, v129
	v_mov_b32_e32 v129, v128
	s_nop 1
	v_permlane32_swap_b32 v129, v128
	s_and_saveexec_b64 s[12:13], s[4:5]
	s_cbranch_execz .LBB0_2287
	s_lshl_b32 s14, s2, 10
	s_add_i32 s14, s3, s14
	v_lshl_add_u32 v130, v195, 4, s14
	s_waitcnt lgkmcnt(0)
	v_add_f32_e32 v128, v128, v129
	ds_write_b32 v130, v128 offset:2048
.LBB0_2287:
	s_or_b64 exec, exec, s[12:13]
	v_mul_f32_e32 v128, v45, v45
	s_waitcnt lgkmcnt(0)
	v_mul_f32_e32 v129, v47, v47
	v_fmac_f32_e32 v128, v44, v44
	v_fmac_f32_e32 v129, v46, v46
	v_add_f32_e32 v128, v128, v129
	v_mul_f32_e32 v129, v41, v41
	v_mul_f32_e32 v130, v43, v43
	v_fmac_f32_e32 v129, v40, v40
	v_fmac_f32_e32 v130, v42, v42
	v_add_f32_e32 v129, v129, v130
	v_add_f32_e32 v128, v128, v129
	v_mul_f32_e32 v129, v37, v37
	v_mul_f32_e32 v130, v39, v39
	v_fmac_f32_e32 v129, v36, v36
	v_fmac_f32_e32 v130, v38, v38
	v_add_f32_e32 v129, v129, v130
	v_add_f32_e32 v128, v129, v128
	v_mul_f32_e32 v129, v33, v33
	v_mul_f32_e32 v130, v35, v35
	v_fmac_f32_e32 v129, v32, v32
	v_fmac_f32_e32 v130, v34, v34
	v_add_f32_e32 v129, v129, v130
	v_add_f32_e32 v128, v129, v128
	v_mov_b32_e32 v129, v128
	s_nop 1
	v_permlane16_swap_b32 v129, v128
	s_waitcnt lgkmcnt(0)
	v_add_f32_e32 v128, v128, v129
	v_mov_b32_e32 v129, v128
	s_nop 1
	v_permlane32_swap_b32 v129, v128
	s_and_saveexec_b64 s[12:13], s[4:5]
	s_cbranch_execz .LBB0_2289
	s_lshl_b32 s14, s2, 10
	s_add_i32 s14, s3, s14
	v_lshl_add_u32 v130, v195, 4, s14
	s_waitcnt lgkmcnt(0)
	v_add_f32_e32 v128, v128, v129
	ds_write_b32 v130, v128 offset:2304
.LBB0_2289:
	s_or_b64 exec, exec, s[12:13]
	v_mul_f32_e32 v128, v29, v29
	s_waitcnt lgkmcnt(0)
	v_mul_f32_e32 v129, v31, v31
	v_fmac_f32_e32 v128, v28, v28
	v_fmac_f32_e32 v129, v30, v30
	v_add_f32_e32 v128, v128, v129
	v_mul_f32_e32 v129, v25, v25
	v_mul_f32_e32 v130, v27, v27
	v_fmac_f32_e32 v129, v24, v24
	v_fmac_f32_e32 v130, v26, v26
	v_add_f32_e32 v129, v129, v130
	v_add_f32_e32 v128, v128, v129
	v_mul_f32_e32 v129, v21, v21
	v_mul_f32_e32 v130, v23, v23
	v_fmac_f32_e32 v129, v20, v20
	v_fmac_f32_e32 v130, v22, v22
	v_add_f32_e32 v129, v129, v130
	v_add_f32_e32 v128, v129, v128
	v_mul_f32_e32 v129, v17, v17
	v_mul_f32_e32 v130, v19, v19
	v_fmac_f32_e32 v129, v16, v16
	v_fmac_f32_e32 v130, v18, v18
	v_add_f32_e32 v129, v129, v130
	v_add_f32_e32 v128, v129, v128
	v_mov_b32_e32 v129, v128
	s_nop 1
	v_permlane16_swap_b32 v129, v128
	s_waitcnt lgkmcnt(0)
	v_add_f32_e32 v128, v128, v129
	v_mov_b32_e32 v129, v128
	s_nop 1
	v_permlane32_swap_b32 v129, v128
	s_and_saveexec_b64 s[12:13], s[4:5]
	s_cbranch_execz .LBB0_2291
	s_lshl_b32 s14, s2, 10
	s_add_i32 s14, s3, s14
	v_lshl_add_u32 v130, v195, 4, s14
	s_waitcnt lgkmcnt(0)
	v_add_f32_e32 v128, v128, v129
	ds_write_b32 v130, v128 offset:2560
.LBB0_2291:
	s_or_b64 exec, exec, s[12:13]
	v_mul_f32_e32 v128, v13, v13
	s_waitcnt lgkmcnt(0)
	v_mul_f32_e32 v129, v15, v15
	v_fmac_f32_e32 v128, v12, v12
	v_fmac_f32_e32 v129, v14, v14
	v_add_f32_e32 v128, v128, v129
	v_mul_f32_e32 v129, v9, v9
	v_mul_f32_e32 v130, v11, v11
	v_fmac_f32_e32 v129, v8, v8
	v_fmac_f32_e32 v130, v10, v10
	v_add_f32_e32 v129, v129, v130
	v_add_f32_e32 v128, v128, v129
	v_mul_f32_e32 v129, v5, v5
	v_mul_f32_e32 v130, v7, v7
	v_fmac_f32_e32 v129, v4, v4
	v_fmac_f32_e32 v130, v6, v6
	v_add_f32_e32 v129, v129, v130
	v_add_f32_e32 v128, v129, v128
	v_mul_f32_e32 v129, v1, v1
	v_mul_f32_e32 v130, v3, v3
	v_fmac_f32_e32 v129, v0, v0
	v_fmac_f32_e32 v130, v2, v2
	v_add_f32_e32 v129, v129, v130
	v_add_f32_e32 v128, v129, v128
	v_mov_b32_e32 v129, v128
	s_nop 1
	v_permlane16_swap_b32 v129, v128
	s_waitcnt lgkmcnt(0)
	v_add_f32_e32 v128, v128, v129
	v_mov_b32_e32 v129, v128
	s_nop 1
	v_permlane32_swap_b32 v129, v128
	s_and_saveexec_b64 s[12:13], s[4:5]
	s_cbranch_execz .LBB0_2293
	s_lshl_b32 s2, s2, 10
	s_add_i32 s3, s3, s2
	v_lshl_add_u32 v130, v195, 4, s3
	s_waitcnt lgkmcnt(0)
	v_add_f32_e32 v128, v128, v129
	ds_write_b32 v130, v128 offset:2816
